# GEMM K-loop: first iteration peeled with SrcC=0 on first-touch MFMAs, accumulator zeroing removed
# speedup vs baseline: 1.0196x; 1.0058x over previous
; #define PG8_STAGE(bufoff, gbase, voff) do { _Pragma("unroll") for (int _i = 0; _i < 2; ++_i) \
;         __builtin_amdgcn_global_load_lds((const unsigned*)((const char*)(gbase) + (voff)[_i]), (PG8_LAS unsigned*)(lds + (bufoff) + ldsw + _i * 8192), 16, 0, 0); } while (0)
; #define PG8_LDA(dst, b, h) do { _Pragma("unroll") for (int m = 0; m < 4; ++m) _Pragma("unroll") for (int k = 0; k < 2; ++k) dst[m][k] = *(const PG8_LAS bf16x8*)(lds + PG8_SA(b, h) + aoff + m * 2048 + k * 1024); } while (0)
; #define PG8_LDB(dst, b, h) do { _Pragma("unroll") for (int n = 0; n < 2; ++n) _Pragma("unroll") for (int k = 0; k < 2; ++k) dst[n][k] = *(const PG8_LAS bf16x8*)(lds + PG8_SB(b, h) + boff + n * 2048 + k * 1024); } while (0)
; #define PG8_MMA(ai, bj, At, Bt) do { __builtin_amdgcn_s_setprio(1); _Pragma("unroll") for (int m = 0; m < 4; ++m) _Pragma("unroll") for (int n = 0; n < 2; ++n) _Pragma("unroll") for (int k = 0; k < 2; ++k) \
;         acc[ai][bj][m][n] = __builtin_amdgcn_mfma_f32_16x16x32_bf16(Bt[n][k], At[m][k], acc[ai][bj][m][n], 0, 0, 0); __builtin_amdgcn_s_setprio(0); } while (0)
; #define PG8_WAIT_V(n) asm volatile("s_waitcnt vmcnt(" #n ")" ::: "memory")
; #define PG8_WAIT_L(n) asm volatile("s_waitcnt lgkmcnt(" #n ")" ::: "memory")
; template <class Epi, class Sched, bool ALIGN_EPI = false, bool SP2 = false>
; __device__ __forceinline__ void gemm_phase(PG8_LAS unsigned char* lds, const Gemm g, const Sched& S, const Epi& E) {
;     ...
;             const char* a1 = cA + (size_t)(t + 1) * kstepA;
;             const char* a2 = last ? nA : cA + (size_t)(t + 2) * kstepA; const char* b2 = last ? nB : cB + (size_t)(t + 2) * kstepB;
;             const char* a3 = a2 + kstepA; const char* b3 = b2 + kstepB;
;             if (last && has_next) { S.a_ready(nxt); E.prefetch(nxt, ui + 1, tid); }
;             if constexpr (SP2) {
;             PG8_LDB(B0, 0, 0); PG8_LDB(B1, 0, 1); PG8_SCHED; PG8_LDA(At, 0, 0); PG8_STAGE(PG8_SA(1, 1), a1 + hstepA, voffA);
;             PG8_WAIT_V(8); PG8_WAIT_L(0); PG8_BAR; PG8_MMA(0, 0, At, B0); PG8_MMA(0, 1, At, B1); PG8_BAR; PG8_SCHED;
;             PG8_LDA(At, 0, 1); PG8_STAGE(PG8_SB(0, 0), b2, voffB); PG8_STAGE(PG8_SB(0, 1), b2 + hstepB, voffB); PG8_STAGE(PG8_SA(0, 0), a2, voffA);
;             PG8_WAIT_V(8); PG8_WAIT_L(0); PG8_BAR; PG8_MMA(1, 0, At, B0); PG8_MMA(1, 1, At, B1); PG8_BAR; PG8_SCHED;
.LBB0_505:
	s_add_u32 s31, s2, s45
	s_addc_u32 s36, s3, s44
	s_lshl_b32 s16, s80, 8
	v_add_u32_e32 v2, s16, v1
	v_ashrrev_i32_e32 v3, 31, v2
	v_add_u32_e32 v4, s16, v232
	s_lshl_b32 s16, s43, 10
	v_lshlrev_b64 v[2:3], 7, v[2:3]
	v_ashrrev_i32_e32 v5, 31, v4
	s_and_b32 s16, s16, 0x400
	v_lshlrev_b64 v[4:5], 7, v[4:5]
	s_waitcnt lgkmcnt(0)
	v_lshl_add_u64 v[130:131], v[196:197], 0, v[2:3]
	s_add_u32 s39, s14, 0x10000
	v_add_u32_e32 v134, s16, v240
	v_lshl_add_u64 v[132:133], v[196:197], 0, v[4:5]
	v_add_u32_e32 v135, s16, v241
	s_addc_u32 s50, s15, 0
	s_mov_b64 s[14:15], 0
	s_mov_b64 s[16:17], 0
	s_add_u32 s18, s14, 1
	s_addc_u32 s19, s15, 0
	s_lshl_b64 s[60:61], s[18:19], s48
	s_add_u32 s14, s14, 2
	s_addc_u32 s15, s15, 0
	s_lshl_b64 s[18:19], s[14:15], s48
	s_add_u32 s18, s2, s18
	s_addc_u32 s19, s3, s19
	s_and_b64 s[16:17], s[16:17], exec
	s_cselect_b32 s24, s52, s18
	s_cselect_b32 s25, s53, s19
	s_cselect_b32 s19, s55, s50
	s_cselect_b32 s18, s54, s39
	s_add_u32 s16, s24, s35
	s_addc_u32 s17, s25, 0
	s_add_u32 s20, s18, 0x8000
	s_addc_u32 s21, s19, 0
	s_add_i32 s51, 0, 0x10000
	s_add_i32 s72, 0, 0x14000
	v_add_u32_e32 v148, s51, v195
	v_add_u32_e32 v164, s72, v195
	s_waitcnt lgkmcnt(0)
	ds_read_b128 v[136:139], v148
	ds_read_b128 v[140:143], v148 offset:1024
	ds_read_b128 v[144:147], v148 offset:2048
	ds_read_b128 v[148:151], v148 offset:3072
	ds_read_b128 v[152:155], v164
	ds_read_b128 v[156:159], v164 offset:1024
	ds_read_b128 v[160:163], v164 offset:2048
	ds_read_b128 v[164:167], v164 offset:3072
	s_add_u32 s60, s31, s60
	s_addc_u32 s61, s36, s61
	v_lshl_add_u64 v[180:181], s[60:61], 0, v[184:185]
	s_add_i32 m0, s63, 0xc000
	ds_read_b128 v[168:171], v242
	ds_read_b128 v[172:175], v242 offset:1024
	ds_read_b128 v[176:179], v242 offset:2048
	ds_read_b128 v[200:203], v242 offset:3072
	ds_read_b128 v[204:207], v242 offset:4096
	ds_read_b128 v[208:211], v242 offset:5120
	ds_read_b128 v[212:215], v242 offset:6144
	ds_read_b128 v[244:247], v242 offset:7168
	global_load_lds_dwordx4 v[180:181], off
	v_lshl_add_u64 v[180:181], s[60:61], 0, v[188:189]
	s_add_i32 m0, s63, 0xe000
	s_nop 0
	global_load_lds_dwordx4 v[180:181], off
	s_waitcnt vmcnt(8)
	s_waitcnt lgkmcnt(0)
	s_barrier
	s_setprio 1
	s_waitcnt lgkmcnt(0)
	v_mfma_f32_16x16x32_bf16 v[126:129], v[136:139], v[168:171], 0
	v_mfma_f32_16x16x32_bf16 v[118:121], v[144:147], v[168:171], 0
	v_mfma_f32_16x16x32_bf16 v[110:113], v[136:139], v[176:179], 0
	v_mfma_f32_16x16x32_bf16 v[102:105], v[144:147], v[176:179], 0
	v_mfma_f32_16x16x32_bf16 v[94:97], v[136:139], v[204:207], 0
	v_mfma_f32_16x16x32_bf16 v[86:89], v[144:147], v[204:207], 0
	v_mfma_f32_16x16x32_bf16 v[78:81], v[136:139], v[212:215], 0
	v_mfma_f32_16x16x32_bf16 v[70:73], v[144:147], v[212:215], 0
	v_mfma_f32_16x16x32_bf16 v[126:129], v[140:143], v[172:175], v[126:129]
	v_mfma_f32_16x16x32_bf16 v[118:121], v[148:151], v[172:175], v[118:121]
	v_mfma_f32_16x16x32_bf16 v[110:113], v[140:143], v[200:203], v[110:113]
	v_mfma_f32_16x16x32_bf16 v[102:105], v[148:151], v[200:203], v[102:105]
	v_mfma_f32_16x16x32_bf16 v[94:97], v[140:143], v[208:211], v[94:97]
	v_mfma_f32_16x16x32_bf16 v[86:89], v[148:151], v[208:211], v[86:89]
	v_mfma_f32_16x16x32_bf16 v[78:81], v[140:143], v[244:247], v[78:81]
	v_mfma_f32_16x16x32_bf16 v[70:73], v[148:151], v[244:247], v[70:73]
	s_setprio 0
	s_setprio 1
	v_mfma_f32_16x16x32_bf16 v[122:125], v[152:155], v[168:171], 0
	v_mfma_f32_16x16x32_bf16 v[114:117], v[160:163], v[168:171], 0
	v_mfma_f32_16x16x32_bf16 v[106:109], v[152:155], v[176:179], 0
	v_mfma_f32_16x16x32_bf16 v[98:101], v[160:163], v[176:179], 0
	v_mfma_f32_16x16x32_bf16 v[90:93], v[152:155], v[204:207], 0
	v_mfma_f32_16x16x32_bf16 v[82:85], v[160:163], v[204:207], 0
	v_mfma_f32_16x16x32_bf16 v[74:77], v[152:155], v[212:215], 0
	v_mfma_f32_16x16x32_bf16 v[66:69], v[160:163], v[212:215], 0
	v_mfma_f32_16x16x32_bf16 v[122:125], v[156:159], v[172:175], v[122:125]
	v_mfma_f32_16x16x32_bf16 v[114:117], v[164:167], v[172:175], v[114:117]
	v_mfma_f32_16x16x32_bf16 v[106:109], v[156:159], v[200:203], v[106:109]
	v_mfma_f32_16x16x32_bf16 v[98:101], v[164:167], v[200:203], v[98:101]
	v_mfma_f32_16x16x32_bf16 v[90:93], v[156:159], v[208:211], v[90:93]
	v_mfma_f32_16x16x32_bf16 v[82:85], v[164:167], v[208:211], v[82:85]
	s_setprio 2
	s_barrier
	v_mfma_f32_16x16x32_bf16 v[74:77], v[156:159], v[244:247], v[74:77]
	v_mfma_f32_16x16x32_bf16 v[66:69], v[164:167], v[244:247], v[66:69]
	s_setprio 0
	s_add_i32 s51, s51, s62
	v_lshl_add_u64 v[180:181], s[18:19], 0, v[186:187]
	s_mov_b32 m0, s51
	ds_read_b128 v[168:171], v242 offset:16384
	ds_read_b128 v[172:175], v242 offset:17408
	ds_read_b128 v[176:179], v242 offset:18432
	ds_read_b128 v[200:203], v242 offset:19456
	ds_read_b128 v[204:207], v242 offset:20480
	ds_read_b128 v[208:211], v242 offset:21504
	ds_read_b128 v[212:215], v242 offset:22528
	ds_read_b128 v[244:247], v242 offset:23552
	global_load_lds_dwordx4 v[180:181], off
	s_add_i32 m0, s51, 0x2000
	s_add_u32 s60, s18, 0x4000
	v_lshl_add_u64 v[180:181], s[18:19], 0, v[190:191]
	s_addc_u32 s61, s19, 0
	s_add_i32 s51, s72, s62
	global_load_lds_dwordx4 v[180:181], off
	v_lshl_add_u64 v[180:181], s[60:61], 0, v[186:187]
	s_mov_b32 m0, s51
	s_nop 0
	global_load_lds_dwordx4 v[180:181], off
	v_lshl_add_u64 v[180:181], s[60:61], 0, v[190:191]
	s_add_i32 m0, s51, 0x2000
	s_nop 0
	global_load_lds_dwordx4 v[180:181], off
	v_lshl_add_u64 v[180:181], s[24:25], 0, v[184:185]
	s_mov_b32 m0, s63
	s_nop 0
	global_load_lds_dwordx4 v[180:181], off
	v_lshl_add_u64 v[180:181], s[24:25], 0, v[188:189]
	s_mov_b32 m0, s28
	s_nop 0
	global_load_lds_dwordx4 v[180:181], off
	s_waitcnt vmcnt(8)
	s_waitcnt lgkmcnt(0)
	s_barrier
; #define PG8_STAGE(bufoff, gbase, voff) do { _Pragma("unroll") for (int _i = 0; _i < 2; ++_i) \
;         __builtin_amdgcn_global_load_lds((const unsigned*)((const char*)(gbase) + (voff)[_i]), (PG8_LAS unsigned*)(lds + (bufoff) + ldsw + _i * 8192), 16, 0, 0); } while (0)
; #define PG8_LDA(dst, b, h) do { _Pragma("unroll") for (int m = 0; m < 4; ++m) _Pragma("unroll") for (int k = 0; k < 2; ++k) dst[m][k] = *(const PG8_LAS bf16x8*)(lds + PG8_SA(b, h) + aoff + m * 2048 + k * 1024); } while (0)
; #define PG8_LDB(dst, b, h) do { _Pragma("unroll") for (int n = 0; n < 2; ++n) _Pragma("unroll") for (int k = 0; k < 2; ++k) dst[n][k] = *(const PG8_LAS bf16x8*)(lds + PG8_SB(b, h) + boff + n * 2048 + k * 1024); } while (0)
; #define PG8_MMA(ai, bj, At, Bt) do { __builtin_amdgcn_s_setprio(1); _Pragma("unroll") for (int m = 0; m < 4; ++m) _Pragma("unroll") for (int n = 0; n < 2; ++n) _Pragma("unroll") for (int k = 0; k < 2; ++k) \
;         acc[ai][bj][m][n] = __builtin_amdgcn_mfma_f32_16x16x32_bf16(Bt[n][k], At[m][k], acc[ai][bj][m][n], 0, 0, 0); __builtin_amdgcn_s_setprio(0); } while (0)
; #define PG8_WAIT_V(n) asm volatile("s_waitcnt vmcnt(" #n ")" ::: "memory")
; #define PG8_WAIT_L(n) asm volatile("s_waitcnt lgkmcnt(" #n ")" ::: "memory")
; #define PG8_BAR __builtin_amdgcn_s_barrier()
; #define PG8_SCHED __builtin_amdgcn_sched_barrier(0)
; template <class Epi, class Sched, bool ALIGN_EPI = false, bool SP2 = false>
; __device__ __forceinline__ void gemm_phase(PG8_LAS unsigned char* lds, const Gemm g, const Sched& S, const Epi& E) {
;     ...
;             PG8_WAIT_V(8); PG8_WAIT_L(0); PG8_BAR; PG8_MMA(1, 0, At, B0); PG8_MMA(1, 1, At, B1); PG8_BAR; PG8_SCHED;
;             PG8_LDB(B0, 1, 0); PG8_LDB(B1, 1, 1); PG8_SCHED; PG8_LDA(At, 1, 0); PG8_STAGE(PG8_SA(0, 1), a2 + hstepA, voffA);
;             PG8_WAIT_V(8); PG8_WAIT_L(0); PG8_BAR; PG8_MMA(0, 0, At, B0); PG8_MMA(0, 1, At, B1); PG8_BAR; PG8_SCHED;
	s_setprio 1
	s_waitcnt lgkmcnt(0)
	v_mfma_f32_16x16x32_bf16 v[62:65], v[136:139], v[168:171], 0
	v_mfma_f32_16x16x32_bf16 v[54:57], v[144:147], v[168:171], 0
	v_mfma_f32_16x16x32_bf16 v[46:49], v[136:139], v[176:179], 0
	v_mfma_f32_16x16x32_bf16 v[38:41], v[144:147], v[176:179], 0
	v_mfma_f32_16x16x32_bf16 v[30:33], v[136:139], v[204:207], 0
	v_mfma_f32_16x16x32_bf16 v[22:25], v[144:147], v[204:207], 0
	v_mfma_f32_16x16x32_bf16 v[14:17], v[136:139], v[212:215], 0
	v_mfma_f32_16x16x32_bf16 v[6:9], v[144:147], v[212:215], 0
	v_mfma_f32_16x16x32_bf16 v[62:65], v[140:143], v[172:175], v[62:65]
	v_mfma_f32_16x16x32_bf16 v[54:57], v[148:151], v[172:175], v[54:57]
	v_mfma_f32_16x16x32_bf16 v[46:49], v[140:143], v[200:203], v[46:49]
	v_mfma_f32_16x16x32_bf16 v[38:41], v[148:151], v[200:203], v[38:41]
	v_mfma_f32_16x16x32_bf16 v[30:33], v[140:143], v[208:211], v[30:33]
	v_mfma_f32_16x16x32_bf16 v[22:25], v[148:151], v[208:211], v[22:25]
	v_mfma_f32_16x16x32_bf16 v[14:17], v[140:143], v[244:247], v[14:17]
	v_mfma_f32_16x16x32_bf16 v[6:9], v[148:151], v[244:247], v[6:9]
	s_setprio 0
	s_setprio 1
	v_mfma_f32_16x16x32_bf16 v[58:61], v[152:155], v[168:171], 0
	v_mfma_f32_16x16x32_bf16 v[50:53], v[160:163], v[168:171], 0
	v_mfma_f32_16x16x32_bf16 v[42:45], v[152:155], v[176:179], 0
	v_mfma_f32_16x16x32_bf16 v[34:37], v[160:163], v[176:179], 0
	v_mfma_f32_16x16x32_bf16 v[26:29], v[152:155], v[204:207], 0
	v_mfma_f32_16x16x32_bf16 v[18:21], v[160:163], v[204:207], 0
	v_mfma_f32_16x16x32_bf16 v[10:13], v[152:155], v[212:215], 0
	v_mfma_f32_16x16x32_bf16 v[2:5], v[160:163], v[212:215], 0
	v_mfma_f32_16x16x32_bf16 v[58:61], v[156:159], v[172:175], v[58:61]
	v_mfma_f32_16x16x32_bf16 v[50:53], v[164:167], v[172:175], v[50:53]
	v_mfma_f32_16x16x32_bf16 v[42:45], v[156:159], v[200:203], v[42:45]
	v_mfma_f32_16x16x32_bf16 v[34:37], v[164:167], v[200:203], v[34:37]
	v_mfma_f32_16x16x32_bf16 v[26:29], v[156:159], v[208:211], v[26:29]
	v_mfma_f32_16x16x32_bf16 v[18:21], v[164:167], v[208:211], v[18:21]
	s_setprio 2
	s_barrier
	v_mfma_f32_16x16x32_bf16 v[10:13], v[156:159], v[244:247], v[10:13]
	v_mfma_f32_16x16x32_bf16 v[2:5], v[164:167], v[244:247], v[2:5]
	s_setprio 0
	s_add_i32 s51, 0, 0x18000
	s_add_i32 s60, 0, 0x1c000
	v_add_u32_e32 v148, s51, v195
	v_add_u32_e32 v164, s60, v195
	ds_read_b128 v[136:139], v148
	ds_read_b128 v[140:143], v148 offset:1024
	ds_read_b128 v[144:147], v148 offset:2048
	ds_read_b128 v[148:151], v148 offset:3072
	ds_read_b128 v[152:155], v164
	ds_read_b128 v[156:159], v164 offset:1024
	ds_read_b128 v[160:163], v164 offset:2048
	ds_read_b128 v[164:167], v164 offset:3072
	s_add_u32 s24, s24, s45
	s_addc_u32 s25, s25, s44
	s_mov_b32 m0, s29
	v_lshl_add_u64 v[180:181], s[24:25], 0, v[184:185]
	ds_read_b128 v[168:171], v242 offset:32768
	ds_read_b128 v[172:175], v242 offset:33792
	ds_read_b128 v[176:179], v242 offset:34816
	ds_read_b128 v[200:203], v242 offset:35840
	ds_read_b128 v[204:207], v242 offset:36864
	ds_read_b128 v[208:211], v242 offset:37888
	ds_read_b128 v[212:215], v242 offset:38912
	ds_read_b128 v[244:247], v242 offset:39936
	global_load_lds_dwordx4 v[180:181], off
	v_lshl_add_u64 v[180:181], s[24:25], 0, v[188:189]
	s_mov_b32 m0, s26
	s_nop 0
	global_load_lds_dwordx4 v[180:181], off
	s_waitcnt vmcnt(8)
	s_waitcnt lgkmcnt(0)
	s_barrier
	s_setprio 1
	s_waitcnt lgkmcnt(0)
	v_mfma_f32_16x16x32_bf16 v[126:129], v[136:139], v[168:171], v[126:129]
	v_mfma_f32_16x16x32_bf16 v[118:121], v[144:147], v[168:171], v[118:121]
	v_mfma_f32_16x16x32_bf16 v[110:113], v[136:139], v[176:179], v[110:113]
	v_mfma_f32_16x16x32_bf16 v[102:105], v[144:147], v[176:179], v[102:105]
	v_mfma_f32_16x16x32_bf16 v[94:97], v[136:139], v[204:207], v[94:97]
	v_mfma_f32_16x16x32_bf16 v[86:89], v[144:147], v[204:207], v[86:89]
	v_mfma_f32_16x16x32_bf16 v[78:81], v[136:139], v[212:215], v[78:81]
	v_mfma_f32_16x16x32_bf16 v[70:73], v[144:147], v[212:215], v[70:73]
	v_mfma_f32_16x16x32_bf16 v[126:129], v[140:143], v[172:175], v[126:129]
	v_mfma_f32_16x16x32_bf16 v[118:121], v[148:151], v[172:175], v[118:121]
	v_mfma_f32_16x16x32_bf16 v[110:113], v[140:143], v[200:203], v[110:113]
	v_mfma_f32_16x16x32_bf16 v[102:105], v[148:151], v[200:203], v[102:105]
	v_mfma_f32_16x16x32_bf16 v[94:97], v[140:143], v[208:211], v[94:97]
	v_mfma_f32_16x16x32_bf16 v[86:89], v[148:151], v[208:211], v[86:89]
	v_mfma_f32_16x16x32_bf16 v[78:81], v[140:143], v[244:247], v[78:81]
	v_mfma_f32_16x16x32_bf16 v[70:73], v[148:151], v[244:247], v[70:73]
	s_setprio 0
	s_setprio 1
	v_mfma_f32_16x16x32_bf16 v[122:125], v[152:155], v[168:171], v[122:125]
	v_mfma_f32_16x16x32_bf16 v[114:117], v[160:163], v[168:171], v[114:117]
	v_mfma_f32_16x16x32_bf16 v[106:109], v[152:155], v[176:179], v[106:109]
	v_mfma_f32_16x16x32_bf16 v[98:101], v[160:163], v[176:179], v[98:101]
	v_mfma_f32_16x16x32_bf16 v[90:93], v[152:155], v[204:207], v[90:93]
	v_mfma_f32_16x16x32_bf16 v[82:85], v[160:163], v[204:207], v[82:85]
	v_mfma_f32_16x16x32_bf16 v[74:77], v[152:155], v[212:215], v[74:77]
	v_mfma_f32_16x16x32_bf16 v[66:69], v[160:163], v[212:215], v[66:69]
	v_mfma_f32_16x16x32_bf16 v[122:125], v[156:159], v[172:175], v[122:125]
	v_mfma_f32_16x16x32_bf16 v[114:117], v[164:167], v[172:175], v[114:117]
	v_mfma_f32_16x16x32_bf16 v[106:109], v[156:159], v[200:203], v[106:109]
	v_mfma_f32_16x16x32_bf16 v[98:101], v[164:167], v[200:203], v[98:101]
	v_mfma_f32_16x16x32_bf16 v[90:93], v[156:159], v[208:211], v[90:93]
	v_mfma_f32_16x16x32_bf16 v[82:85], v[164:167], v[208:211], v[82:85]
	s_setprio 2
	s_barrier
; #define PG8_STAGE(bufoff, gbase, voff) do { _Pragma("unroll") for (int _i = 0; _i < 2; ++_i) \
;         __builtin_amdgcn_global_load_lds((const unsigned*)((const char*)(gbase) + (voff)[_i]), (PG8_LAS unsigned*)(lds + (bufoff) + ldsw + _i * 8192), 16, 0, 0); } while (0)
; #define PG8_LDA(dst, b, h) do { _Pragma("unroll") for (int m = 0; m < 4; ++m) _Pragma("unroll") for (int k = 0; k < 2; ++k) dst[m][k] = *(const PG8_LAS bf16x8*)(lds + PG8_SA(b, h) + aoff + m * 2048 + k * 1024); } while (0)
; #define PG8_MMA(ai, bj, At, Bt) do { __builtin_amdgcn_s_setprio(1); _Pragma("unroll") for (int m = 0; m < 4; ++m) _Pragma("unroll") for (int n = 0; n < 2; ++n) _Pragma("unroll") for (int k = 0; k < 2; ++k) \
;         acc[ai][bj][m][n] = __builtin_amdgcn_mfma_f32_16x16x32_bf16(Bt[n][k], At[m][k], acc[ai][bj][m][n], 0, 0, 0); __builtin_amdgcn_s_setprio(0); } while (0)
; #define PG8_WAIT_V(n) asm volatile("s_waitcnt vmcnt(" #n ")" ::: "memory")
; #define PG8_WAIT_L(n) asm volatile("s_waitcnt lgkmcnt(" #n ")" ::: "memory")
; #define PG8_BAR __builtin_amdgcn_s_barrier()
; #define PG8_SCHED __builtin_amdgcn_sched_barrier(0)
; template <class Epi, class Sched, bool ALIGN_EPI = false, bool SP2 = false>
; __device__ __forceinline__ void gemm_phase(PG8_LAS unsigned char* lds, const Gemm g, const Sched& S, const Epi& E) {
;     ...
;             PG8_LDA(At, 1, 1); PG8_STAGE(PG8_SB(1, 0), b3, voffB); PG8_STAGE(PG8_SB(1, 1), b3 + hstepB, voffB); PG8_STAGE(PG8_SA(1, 0), a3, voffA);
;             PG8_WAIT_V(8); PG8_WAIT_L(0); PG8_BAR; PG8_MMA(1, 0, At, B0); PG8_MMA(1, 1, At, B1); PG8_BAR; PG8_SCHED;
	v_mfma_f32_16x16x32_bf16 v[74:77], v[156:159], v[244:247], v[74:77]
	v_mfma_f32_16x16x32_bf16 v[66:69], v[164:167], v[244:247], v[66:69]
	s_setprio 0
	s_add_i32 s24, s51, s62
	v_lshl_add_u64 v[180:181], s[20:21], 0, v[186:187]
	s_mov_b32 m0, s24
	ds_read_b128 v[168:171], v242 offset:49152
	ds_read_b128 v[172:175], v242 offset:50176
	ds_read_b128 v[176:179], v242 offset:51200
	ds_read_b128 v[200:203], v242 offset:52224
	ds_read_b128 v[204:207], v242 offset:53248
	ds_read_b128 v[208:211], v242 offset:54272
	ds_read_b128 v[212:215], v242 offset:55296
	ds_read_b128 v[244:247], v242 offset:56320
	global_load_lds_dwordx4 v[180:181], off
	s_add_i32 m0, s24, 0x2000
	s_add_u32 s18, s18, 0xc000
	v_lshl_add_u64 v[180:181], s[20:21], 0, v[190:191]
	s_addc_u32 s19, s19, 0
	s_add_i32 s20, s60, s62
	global_load_lds_dwordx4 v[180:181], off
	v_lshl_add_u64 v[180:181], s[18:19], 0, v[186:187]
	s_mov_b32 m0, s20
	s_nop 0
	global_load_lds_dwordx4 v[180:181], off
	v_lshl_add_u64 v[180:181], s[18:19], 0, v[190:191]
	s_add_i32 m0, s20, 0x2000
	s_nop 0
	global_load_lds_dwordx4 v[180:181], off
	v_lshl_add_u64 v[180:181], s[16:17], 0, v[184:185]
	s_mov_b32 m0, s1
	s_nop 0
	global_load_lds_dwordx4 v[180:181], off
	v_lshl_add_u64 v[180:181], s[16:17], 0, v[188:189]
	s_mov_b32 m0, s0
	s_nop 0
	global_load_lds_dwordx4 v[180:181], off
	s_waitcnt vmcnt(8)
	s_waitcnt lgkmcnt(0)
	s_barrier
	s_setprio 1
	s_waitcnt lgkmcnt(0)
	v_mfma_f32_16x16x32_bf16 v[62:65], v[136:139], v[168:171], v[62:65]
	v_mfma_f32_16x16x32_bf16 v[54:57], v[144:147], v[168:171], v[54:57]
	v_mfma_f32_16x16x32_bf16 v[46:49], v[136:139], v[176:179], v[46:49]
	v_mfma_f32_16x16x32_bf16 v[38:41], v[144:147], v[176:179], v[38:41]
	v_mfma_f32_16x16x32_bf16 v[30:33], v[136:139], v[204:207], v[30:33]
	v_mfma_f32_16x16x32_bf16 v[22:25], v[144:147], v[204:207], v[22:25]
	v_mfma_f32_16x16x32_bf16 v[14:17], v[136:139], v[212:215], v[14:17]
	v_mfma_f32_16x16x32_bf16 v[6:9], v[144:147], v[212:215], v[6:9]
	v_mfma_f32_16x16x32_bf16 v[62:65], v[140:143], v[172:175], v[62:65]
	v_mfma_f32_16x16x32_bf16 v[54:57], v[148:151], v[172:175], v[54:57]
	v_mfma_f32_16x16x32_bf16 v[46:49], v[140:143], v[200:203], v[46:49]
	v_mfma_f32_16x16x32_bf16 v[38:41], v[148:151], v[200:203], v[38:41]
	v_mfma_f32_16x16x32_bf16 v[30:33], v[140:143], v[208:211], v[30:33]
	v_mfma_f32_16x16x32_bf16 v[22:25], v[148:151], v[208:211], v[22:25]
	v_mfma_f32_16x16x32_bf16 v[14:17], v[140:143], v[244:247], v[14:17]
	v_mfma_f32_16x16x32_bf16 v[6:9], v[148:151], v[244:247], v[6:9]
	s_setprio 0
	s_setprio 1
	v_mfma_f32_16x16x32_bf16 v[58:61], v[152:155], v[168:171], v[58:61]
	v_mfma_f32_16x16x32_bf16 v[50:53], v[160:163], v[168:171], v[50:53]
	v_mfma_f32_16x16x32_bf16 v[42:45], v[152:155], v[176:179], v[42:45]
	v_mfma_f32_16x16x32_bf16 v[34:37], v[160:163], v[176:179], v[34:37]
	v_mfma_f32_16x16x32_bf16 v[26:29], v[152:155], v[204:207], v[26:29]
	v_mfma_f32_16x16x32_bf16 v[18:21], v[160:163], v[204:207], v[18:21]
	v_mfma_f32_16x16x32_bf16 v[10:13], v[152:155], v[212:215], v[10:13]
	v_mfma_f32_16x16x32_bf16 v[2:5], v[160:163], v[212:215], v[2:5]
	v_mfma_f32_16x16x32_bf16 v[58:61], v[156:159], v[172:175], v[58:61]
	v_mfma_f32_16x16x32_bf16 v[50:53], v[164:167], v[172:175], v[50:53]
	v_mfma_f32_16x16x32_bf16 v[42:45], v[156:159], v[200:203], v[42:45]
	v_mfma_f32_16x16x32_bf16 v[34:37], v[164:167], v[200:203], v[34:37]
	v_mfma_f32_16x16x32_bf16 v[26:29], v[156:159], v[208:211], v[26:29]
	v_mfma_f32_16x16x32_bf16 v[18:21], v[164:167], v[208:211], v[18:21]
	s_setprio 2
	s_barrier
	v_mfma_f32_16x16x32_bf16 v[10:13], v[156:159], v[244:247], v[10:13]
	v_mfma_f32_16x16x32_bf16 v[2:5], v[164:167], v[244:247], v[2:5]
	s_setprio 0
	s_add_u32 s39, s39, 0x10000
	s_addc_u32 s50, s50, 0
	s_branch .LBB0_508
